# MoBA: computing waves raise priority for QK/softmax/PV of a step (staging of skipping waves yields)
# baseline (speedup 1.0000x reference)
.LBB0_151:
	s_ashr_i32 s0, s51, 1
	s_sub_i32 s0, s47, s0
	s_lshl_b32 s0, 1, s0
	s_and_b32 s1, s0, s49
	s_cmp_eq_u32 s1, 0
	s_cbranch_scc1 .LBB0_137
	s_setprio 1
	s_mul_i32 s1, s15, 0x11000
	s_add_i32 s1, s1, 0
	v_add_u32_e32 v84, s1, v167
	v_add_u32_e32 v195, v84, v158
	v_add3_u32 v197, s1, v158, v167
	ds_read_b128 v[108:111], v195
	ds_read_b128 v[104:107], v195 offset:64
	ds_read_b128 v[100:103], v195 offset:128
	ds_read_b128 v[96:99], v195 offset:192
	ds_read_b128 v[92:95], v195 offset:272
	ds_read_b128 v[88:91], v195 offset:336
	ds_read_b128 v[84:87], v195 offset:400
	ds_read_b128 v[198:201], v195 offset:464
	ds_read_b128 v[202:205], v195 offset:8704
	ds_read_b128 v[206:209], v195 offset:8768
	ds_read_b128 v[230:233], v195 offset:8832
	ds_read_b128 v[234:237], v195 offset:8896
	ds_read_b128 v[238:241], v195 offset:8976
	ds_read_b128 v[242:245], v195 offset:9040
	ds_read_b128 v[246:249], v195 offset:9104
	s_waitcnt lgkmcnt(11)
	v_mfma_f32_16x16x32_bf16 v[112:115], v[108:111], v[36:39], 0
	v_mfma_f32_16x16x32_bf16 v[112:115], v[104:107], v[40:43], v[112:115]
	v_mfma_f32_16x16x32_bf16 v[112:115], v[100:103], v[44:47], v[112:115]
	v_mfma_f32_16x16x32_bf16 v[112:115], v[96:99], v[48:51], v[112:115]
	ds_read_b128 v[96:99], v195 offset:9168
	s_waitcnt lgkmcnt(8)
	v_mfma_f32_16x16x32_bf16 v[108:111], v[92:95], v[36:39], 0
	v_mfma_f32_16x16x32_bf16 v[108:111], v[88:91], v[40:43], v[108:111]
	v_mfma_f32_16x16x32_bf16 v[108:111], v[84:87], v[44:47], v[108:111]
	v_mfma_f32_16x16x32_bf16 v[108:111], v[198:201], v[48:51], v[108:111]
	ds_read_b128 v[92:95], v195 offset:17408
	ds_read_b128 v[88:91], v195 offset:17472
	ds_read_b128 v[84:87], v195 offset:17536
	ds_read_b128 v[198:201], v195 offset:17600
	s_waitcnt lgkmcnt(8)
	v_mfma_f32_16x16x32_bf16 v[104:107], v[202:205], v[36:39], 0
	v_mfma_f32_16x16x32_bf16 v[104:107], v[206:209], v[40:43], v[104:107]
	v_mfma_f32_16x16x32_bf16 v[104:107], v[230:233], v[44:47], v[104:107]
	v_mfma_f32_16x16x32_bf16 v[104:107], v[234:237], v[48:51], v[104:107]
	ds_read_b128 v[202:205], v195 offset:17680
	ds_read_b128 v[206:209], v195 offset:17744
	ds_read_b128 v[230:233], v195 offset:17808
	ds_read_b128 v[234:237], v195 offset:17872
	s_waitcnt lgkmcnt(8)
	v_mfma_f32_16x16x32_bf16 v[100:103], v[238:241], v[36:39], 0
	v_mfma_f32_16x16x32_bf16 v[100:103], v[242:245], v[40:43], v[100:103]
	v_mfma_f32_16x16x32_bf16 v[100:103], v[246:249], v[44:47], v[100:103]
	v_mfma_f32_16x16x32_bf16 v[100:103], v[96:99], v[48:51], v[100:103]
	ds_read_b128 v[238:241], v195 offset:26112
	ds_read_b128 v[242:245], v195 offset:26176
	ds_read_b128 v[246:249], v195 offset:26240
	s_waitcnt lgkmcnt(7)
	v_mfma_f32_16x16x32_bf16 v[96:99], v[92:95], v[36:39], 0
	v_mfma_f32_16x16x32_bf16 v[96:99], v[88:91], v[40:43], v[96:99]
	v_mfma_f32_16x16x32_bf16 v[96:99], v[84:87], v[44:47], v[96:99]
	v_mfma_f32_16x16x32_bf16 v[96:99], v[198:201], v[48:51], v[96:99]
	ds_read_b128 v[198:201], v195 offset:26304
	s_waitcnt lgkmcnt(4)
	v_mfma_f32_16x16x32_bf16 v[92:95], v[202:205], v[36:39], 0
	v_mfma_f32_16x16x32_bf16 v[92:95], v[206:209], v[40:43], v[92:95]
	v_mfma_f32_16x16x32_bf16 v[92:95], v[230:233], v[44:47], v[92:95]
	v_mfma_f32_16x16x32_bf16 v[92:95], v[234:237], v[48:51], v[92:95]
	ds_read_b128 v[202:205], v195 offset:26384
	ds_read_b128 v[206:209], v195 offset:26448
	ds_read_b128 v[230:233], v195 offset:26512
	ds_read_b128 v[234:237], v195 offset:26576
	s_waitcnt lgkmcnt(4)
	v_mfma_f32_16x16x32_bf16 v[88:91], v[238:241], v[36:39], 0
	v_mfma_f32_16x16x32_bf16 v[88:91], v[242:245], v[40:43], v[88:91]
	v_mfma_f32_16x16x32_bf16 v[88:91], v[246:249], v[44:47], v[88:91]
	v_mfma_f32_16x16x32_bf16 v[88:91], v[198:201], v[48:51], v[88:91]
	s_waitcnt lgkmcnt(0)
	v_mfma_f32_16x16x32_bf16 v[84:87], v[202:205], v[36:39], 0
	v_mfma_f32_16x16x32_bf16 v[84:87], v[206:209], v[40:43], v[84:87]
	v_mfma_f32_16x16x32_bf16 v[84:87], v[230:233], v[44:47], v[84:87]
	v_mfma_f32_16x16x32_bf16 v[84:87], v[234:237], v[48:51], v[84:87]
	ds_read_b128 v[202:205], v195 offset:34816
	ds_read_b128 v[206:209], v195 offset:35088
	ds_read_b128 v[230:233], v195 offset:43520
	ds_read_b128 v[234:237], v195 offset:43792
	v_and_b32_e32 v197, s0, v139
	v_cmp_eq_u32_e64 s[0:1], 0, v197
	s_cmp_lt_u32 s51, 2
	s_mov_b64 s[10:11], -1
	s_cbranch_scc1 .LBB0_154
	v_max3_f32 v197, v112, v113, v114
	v_max3_f32 v198, v96, v97, v98
	v_max3_f32 v197, v197, v115, v108
	v_max3_f32 v198, v198, v99, v92
	v_max3_f32 v197, v197, v109, v110
	v_max3_f32 v198, v198, v93, v94
	v_max3_f32 v197, v197, v111, v104
	v_max3_f32 v198, v198, v95, v88
	v_max3_f32 v197, v197, v105, v106
	v_max3_f32 v198, v198, v89, v90
	v_max3_f32 v197, v197, v107, v100
	v_max3_f32 v198, v198, v91, v84
	v_max3_f32 v197, v197, v101, v102
	v_max3_f32 v198, v198, v85, v86
	v_max_f32_e32 v197, v197, v103
	v_max_f32_e32 v198, v198, v87
	v_max_f32_e32 v197, v197, v198
	v_cndmask_b32_e64 v197, v197, v215, s[0:1]
	s_mov_b64 s[10:11], 0

.LBB0_158:
	s_waitcnt lgkmcnt(0)
	v_add_f32_e32 v198, v198, v199
	v_fmac_f32_e32 v198, v194, v84
	v_cvt_pk_bf16_f32 v112, v112, v113
	v_cvt_pk_bf16_f32 v113, v114, v115
	v_cvt_pk_bf16_f32 v114, v108, v109
	v_cvt_pk_bf16_f32 v115, v110, v111
	v_cvt_pk_bf16_f32 v104, v104, v105
	v_cvt_pk_bf16_f32 v105, v106, v107
	v_cvt_pk_bf16_f32 v106, v100, v101
	v_cvt_pk_bf16_f32 v107, v102, v103
	v_cvt_pk_bf16_f32 v96, v96, v97
	v_cvt_pk_bf16_f32 v97, v98, v99
	v_cvt_pk_bf16_f32 v98, v92, v93
	v_cvt_pk_bf16_f32 v99, v94, v95
	v_cvt_pk_bf16_f32 v88, v88, v89
	v_cvt_pk_bf16_f32 v89, v90, v91
	v_cvt_pk_bf16_f32 v90, v196, v85
	v_cvt_pk_bf16_f32 v91, v86, v87
	ds_read_b128 v[84:87], v195 offset:52224
	ds_read_b128 v[92:95], v195 offset:52496
	ds_read_b128 v[100:103], v195 offset:60928
	ds_read_b128 v[108:111], v195 offset:61200
	s_waitcnt lgkmcnt(4)
	v_mfma_f32_16x16x32_bf16 v[80:83], v[202:205], v[112:115], v[80:83]
	v_mfma_f32_16x16x32_bf16 v[76:79], v[206:209], v[112:115], v[76:79]
	v_mfma_f32_16x16x32_bf16 v[72:75], v[230:233], v[112:115], v[72:75]
	v_mfma_f32_16x16x32_bf16 v[68:71], v[234:237], v[112:115], v[68:71]
	ds_read_b128 v[202:205], v195 offset:34880
	ds_read_b128 v[206:209], v195 offset:35152
	ds_read_b128 v[230:233], v195 offset:43584
	ds_read_b128 v[234:237], v195 offset:43856
	s_waitcnt lgkmcnt(4)
	v_mfma_f32_16x16x32_bf16 v[64:67], v[84:87], v[112:115], v[64:67]
	v_mfma_f32_16x16x32_bf16 v[60:63], v[92:95], v[112:115], v[60:63]
	v_mfma_f32_16x16x32_bf16 v[56:59], v[100:103], v[112:115], v[56:59]
	v_mfma_f32_16x16x32_bf16 v[52:55], v[108:111], v[112:115], v[52:55]
	ds_read_b128 v[84:87], v195 offset:52288
	ds_read_b128 v[92:95], v195 offset:52560
	ds_read_b128 v[100:103], v195 offset:60992
	ds_read_b128 v[108:111], v195 offset:61264
	s_waitcnt lgkmcnt(4)
	v_mfma_f32_16x16x32_bf16 v[80:83], v[202:205], v[104:107], v[80:83]
	v_mfma_f32_16x16x32_bf16 v[76:79], v[206:209], v[104:107], v[76:79]
	v_mfma_f32_16x16x32_bf16 v[72:75], v[230:233], v[104:107], v[72:75]
	v_mfma_f32_16x16x32_bf16 v[68:71], v[234:237], v[104:107], v[68:71]
	ds_read_b128 v[202:205], v195 offset:34944
	ds_read_b128 v[206:209], v195 offset:35216
	ds_read_b128 v[230:233], v195 offset:43648
	ds_read_b128 v[234:237], v195 offset:43920
	s_waitcnt lgkmcnt(4)
	v_mfma_f32_16x16x32_bf16 v[64:67], v[84:87], v[104:107], v[64:67]
	v_mfma_f32_16x16x32_bf16 v[60:63], v[92:95], v[104:107], v[60:63]
	v_mfma_f32_16x16x32_bf16 v[56:59], v[100:103], v[104:107], v[56:59]
	v_mfma_f32_16x16x32_bf16 v[52:55], v[108:111], v[104:107], v[52:55]
	ds_read_b128 v[84:87], v195 offset:52352
	ds_read_b128 v[92:95], v195 offset:52624
	ds_read_b128 v[100:103], v195 offset:61056
	ds_read_b128 v[108:111], v195 offset:61328
	s_waitcnt lgkmcnt(4)
	v_mfma_f32_16x16x32_bf16 v[80:83], v[202:205], v[96:99], v[80:83]
	v_mfma_f32_16x16x32_bf16 v[76:79], v[206:209], v[96:99], v[76:79]
	v_mfma_f32_16x16x32_bf16 v[72:75], v[230:233], v[96:99], v[72:75]
	v_mfma_f32_16x16x32_bf16 v[68:71], v[234:237], v[96:99], v[68:71]
	ds_read_b128 v[202:205], v195 offset:35008
	ds_read_b128 v[206:209], v195 offset:35280
	ds_read_b128 v[230:233], v195 offset:43712
	ds_read_b128 v[234:237], v195 offset:43984
	s_waitcnt lgkmcnt(4)
	v_mfma_f32_16x16x32_bf16 v[64:67], v[84:87], v[96:99], v[64:67]
	v_mfma_f32_16x16x32_bf16 v[60:63], v[92:95], v[96:99], v[60:63]
	v_mfma_f32_16x16x32_bf16 v[56:59], v[100:103], v[96:99], v[56:59]
	v_mfma_f32_16x16x32_bf16 v[52:55], v[108:111], v[96:99], v[52:55]
	ds_read_b128 v[84:87], v195 offset:52416
	ds_read_b128 v[92:95], v195 offset:52688
	ds_read_b128 v[100:103], v195 offset:61120
	ds_read_b128 v[108:111], v195 offset:61392
	s_waitcnt lgkmcnt(4)
	v_mfma_f32_16x16x32_bf16 v[80:83], v[202:205], v[88:91], v[80:83]
	v_mfma_f32_16x16x32_bf16 v[76:79], v[206:209], v[88:91], v[76:79]
	v_mfma_f32_16x16x32_bf16 v[72:75], v[230:233], v[88:91], v[72:75]
	v_mfma_f32_16x16x32_bf16 v[68:71], v[234:237], v[88:91], v[68:71]
	s_waitcnt lgkmcnt(0)
	v_mfma_f32_16x16x32_bf16 v[64:67], v[84:87], v[88:91], v[64:67]
	v_mfma_f32_16x16x32_bf16 v[60:63], v[92:95], v[88:91], v[60:63]
	v_mfma_f32_16x16x32_bf16 v[56:59], v[100:103], v[88:91], v[56:59]
	v_mfma_f32_16x16x32_bf16 v[52:55], v[108:111], v[88:91], v[52:55]
	v_mov_b32_e32 v194, v198
	s_setprio 0
	s_andn2_b64 vcc, exec, s[8:9]
	s_xor_b32 s15, s15, 1
	s_cbranch_vccnz .LBB0_138
	s_branch .LBB0_92
